# SGU item epilogue: the four u loads issued at item start into attention-only registers (were 4 serial load->vmcnt(0) round trips each also waiting for the previous store ack)
# speedup vs baseline: 1.0088x; 1.0088x over previous
; #define LAS __attribute__((address_space(3)))
; __device__ __forceinline__ void sgu_item(const Params& P, LAS unsigned char* lds, int l, int item) {
;     ...
;     {
;         const int tk = tid >> 2, q = tid & 3;
;         const float bst = P.sgu_b[((size_t)l * NH + h) * 128 + tk];
;         const f16* up = p + (tok0 + tk) * NIN + GW + 128 * h + 32 * q;
;         f16* op = yraw + (tok0 + tk) * DM + GW + 128 * h + 32 * q;
; #pragma unroll
;         for (int i = 0; i < 4; ++i) { const f16x8 u8 = *(const f16x8*)(up + 8 * i);
;             const f32x4 m0 = *(const LAS f32x4*)(mix + tk * 132 + 32 * q + 8 * i), m1 = *(const LAS f32x4*)(mix + tk * 132 + 32 * q + 8 * i + 4);
;             f16x8 o;
; #pragma unroll
;             for (int e = 0; e < 4; ++e) { o[e] = (f16)(gelu_fast((float)u8[e]) * (m0[e] + bst)); o[4 + e] = (f16)(gelu_fast((float)u8[4 + e]) * (m1[e] + bst)); }
;             *(f16x8*)(op + 8 * i) = o; }
.LBB0_883:
	s_waitcnt lgkmcnt(0)
	s_barrier
	v_mov_b32_e32 v12, v109
	v_mov_b32_e32 v13, v207
	v_mov_b32_e32 v14, v209
	v_mov_b32_e32 v15, v211
	s_lshl_b32 s0, s18, 2
	s_add_u32 s0, s54, s0
	s_addc_u32 s1, s55, 0
	v_lshl_add_u64 v[4:5], v[30:31], 2, s[0:1]
	global_load_dword v16, v[4:5], off
	v_lshlrev_b64 v[4:5], 12, v[32:33]
	v_lshl_add_u64 v[4:5], s[90:91], 0, v[4:5]
	s_lshl_b32 s56, s18, 1
	v_lshl_add_u64 v[4:5], v[4:5], 0, s[56:57]
	v_lshlrev_b32_e32 v2, 1, v34
	v_lshl_add_u64 v[32:33], v[4:5], 0, v[2:3]
	v_mul_lo_u32 v2, v30, s4
	v_lshlrev_b32_e32 v4, 2, v34
	v_add3_u32 v2, 0, v2, v4
	ds_read_b128 v[20:23], v2 offset:34816
	ds_read_b128 v[24:27], v2 offset:34832
	ds_read_b128 v[8:11], v2 offset:34848
	ds_read_b128 v[4:7], v2 offset:34864
	s_mov_b64 s[0:1], 0x2dff1400
	v_lshl_add_u64 v[18:19], v[32:33], 0, s[0:1]
	s_mov_b32 s0, 0x2dff1000
	v_readlane_b32 s78, v247, 12
	v_readlane_b32 s79, v247, 13
	s_movk_i32 s76, 0x5ff
	s_mov_b32 s77, 0x13ff1000
	s_waitcnt vmcnt(1)
	v_cvt_f32_f16_e32 v30, v12
	v_cvt_f32_f16_sdwa v31, v12 dst_sel:DWORD dst_unused:UNUSED_PAD src0_sel:WORD_1
	v_mul_f32_e32 v17, 0x3d372713, v30
	v_mul_f32_e32 v17, v17, v30
	v_fma_mix_f32 v17, v17, v12, v12 op_sel_hi:[0,1,1]
	v_mul_f32_e32 v17, 0xc0135761, v17
	v_exp_f32_e32 v17, v17
	s_nop 0
	v_add_f32_e32 v17, 1.0, v17
	v_rcp_f32_e32 v34, v17
	v_mul_f32_e32 v17, 0x3d372713, v31
	v_mul_f32_e32 v17, v17, v31
	v_fma_mix_f32 v12, v17, v12, v12 op_sel:[0,1,1] op_sel_hi:[0,1,1]
	v_mul_f32_e32 v12, 0xc0135761, v12
	v_exp_f32_e32 v12, v12
	s_waitcnt vmcnt(0) lgkmcnt(3)
	v_pk_add_f32 v[20:21], v[16:17], v[20:21] op_sel_hi:[0,1]
	v_add_f32_e32 v12, 1.0, v12
	v_rcp_f32_e32 v35, v12
	s_nop 0
	v_pk_mul_f32 v[30:31], v[34:35], v[30:31]
	s_nop 0
	v_pk_mul_f32 v[20:21], v[20:21], v[30:31]
	s_nop 0
	v_cvt_pk_f16_f32 v12, v20, v21
	v_cvt_f32_f16_e32 v20, v14
	v_cvt_f32_f16_sdwa v21, v14 dst_sel:DWORD dst_unused:UNUSED_PAD src0_sel:WORD_1
	v_mul_f32_e32 v17, 0x3d372713, v20
	v_mul_f32_e32 v17, v17, v20
	v_fma_mix_f32 v17, v17, v14, v14 op_sel_hi:[0,1,1]
	v_mul_f32_e32 v17, 0xc0135761, v17
	v_exp_f32_e32 v17, v17
	s_nop 0
	v_add_f32_e32 v17, 1.0, v17
	v_rcp_f32_e32 v30, v17
	v_mul_f32_e32 v17, 0x3d372713, v21
	v_mul_f32_e32 v17, v17, v21
	v_fma_mix_f32 v14, v17, v14, v14 op_sel:[0,1,1] op_sel_hi:[0,1,1]
	v_mul_f32_e32 v14, 0xc0135761, v14
	v_exp_f32_e32 v14, v14
	s_waitcnt lgkmcnt(2)
	v_pk_add_f32 v[24:25], v[16:17], v[24:25] op_sel_hi:[0,1]
	v_add_f32_e32 v14, 1.0, v14
	v_rcp_f32_e32 v31, v14
	s_nop 0
	v_pk_mul_f32 v[20:21], v[30:31], v[20:21]
	s_nop 0
	v_pk_mul_f32 v[20:21], v[24:25], v[20:21]
	s_nop 0
	v_cvt_pk_f16_f32 v14, v20, v21
	v_cvt_f32_f16_e32 v20, v13
	v_cvt_f32_f16_sdwa v21, v13 dst_sel:DWORD dst_unused:UNUSED_PAD src0_sel:WORD_1
	v_mul_f32_e32 v17, 0x3d372713, v20
	v_mul_f32_e32 v17, v17, v20
	v_fma_mix_f32 v17, v17, v13, v13 op_sel_hi:[0,1,1]
	v_mul_f32_e32 v17, 0xc0135761, v17
	v_exp_f32_e32 v17, v17
	s_nop 0
	v_add_f32_e32 v17, 1.0, v17
	v_rcp_f32_e32 v24, v17
	v_mul_f32_e32 v17, 0x3d372713, v21
	v_mul_f32_e32 v17, v17, v21
	v_fma_mix_f32 v13, v17, v13, v13 op_sel:[0,1,1] op_sel_hi:[0,1,1]
	v_mul_f32_e32 v13, 0xc0135761, v13
	v_exp_f32_e32 v13, v13
	v_pk_add_f32 v[22:23], v[16:17], v[22:23] op_sel_hi:[0,1]
	v_add_f32_e32 v13, 1.0, v13
	v_rcp_f32_e32 v25, v13
	s_nop 0
	v_pk_mul_f32 v[20:21], v[24:25], v[20:21]
	s_nop 0
	v_pk_mul_f32 v[20:21], v[22:23], v[20:21]
	s_nop 0
	v_cvt_pk_f16_f32 v13, v20, v21
	v_cvt_f32_f16_e32 v20, v15
	v_cvt_f32_f16_sdwa v21, v15 dst_sel:DWORD dst_unused:UNUSED_PAD src0_sel:WORD_1
	v_mul_f32_e32 v17, 0x3d372713, v20
	v_mul_f32_e32 v17, v17, v20
	v_fma_mix_f32 v17, v17, v15, v15 op_sel_hi:[0,1,1]
	v_mul_f32_e32 v17, 0xc0135761, v17
	v_exp_f32_e32 v17, v17
	s_nop 0
	v_add_f32_e32 v17, 1.0, v17
	v_rcp_f32_e32 v22, v17
	v_mul_f32_e32 v17, 0x3d372713, v21
	v_mul_f32_e32 v17, v17, v21
	v_fma_mix_f32 v15, v17, v15, v15 op_sel:[0,1,1] op_sel_hi:[0,1,1]
	v_mul_f32_e32 v15, 0xc0135761, v15
	v_exp_f32_e32 v15, v15
	s_nop 0
	v_add_f32_e32 v15, 1.0, v15
	v_rcp_f32_e32 v23, v15
	s_nop 0
	v_pk_mul_f32 v[20:21], v[22:23], v[20:21]
	v_pk_add_f32 v[22:23], v[16:17], v[26:27] op_sel_hi:[0,1]
	v_pk_mul_f32 v[20:21], v[22:23], v[20:21]
	s_nop 0
	v_cvt_pk_f16_f32 v15, v20, v21
	v_add_co_u32_e32 v20, vcc, s0, v32
	s_nop 1
	v_addc_co_u32_e32 v21, vcc, 0, v33, vcc
	global_store_dwordx4 v[20:21], v[12:15], off offset:1024
	s_nop 1
	v_mov_b32_e32 v12, v180
	v_mov_b32_e32 v13, v181
	v_mov_b32_e32 v14, v182
	v_mov_b32_e32 v15, v183
	s_nop 0
	v_cvt_f32_f16_e32 v20, v12
	v_cvt_f32_f16_sdwa v21, v12 dst_sel:DWORD dst_unused:UNUSED_PAD src0_sel:WORD_1
	v_mul_f32_e32 v17, 0x3d372713, v20
	v_mul_f32_e32 v17, v17, v20
	v_fma_mix_f32 v17, v17, v12, v12 op_sel_hi:[0,1,1]
	v_mul_f32_e32 v17, 0xc0135761, v17
	v_exp_f32_e32 v17, v17
	s_nop 0
	v_add_f32_e32 v17, 1.0, v17
	v_rcp_f32_e32 v22, v17
	v_mul_f32_e32 v17, 0x3d372713, v21
	v_mul_f32_e32 v17, v17, v21
	v_fma_mix_f32 v12, v17, v12, v12 op_sel:[0,1,1] op_sel_hi:[0,1,1]
	v_mul_f32_e32 v12, 0xc0135761, v12
	v_exp_f32_e32 v12, v12
	s_waitcnt lgkmcnt(1)
	v_pk_add_f32 v[8:9], v[16:17], v[8:9] op_sel_hi:[0,1]
	v_add_f32_e32 v12, 1.0, v12
	v_rcp_f32_e32 v23, v12
	s_nop 0
	v_pk_mul_f32 v[20:21], v[22:23], v[20:21]
	s_nop 0
	v_pk_mul_f32 v[8:9], v[8:9], v[20:21]
	s_nop 0
	v_cvt_pk_f16_f32 v12, v8, v9
	v_cvt_f32_f16_e32 v8, v14
	v_cvt_f32_f16_sdwa v9, v14 dst_sel:DWORD dst_unused:UNUSED_PAD src0_sel:WORD_1
	v_mul_f32_e32 v17, 0x3d372713, v8
	v_mul_f32_e32 v17, v17, v8
	v_fma_mix_f32 v17, v17, v14, v14 op_sel_hi:[0,1,1]
	v_mul_f32_e32 v17, 0xc0135761, v17
	v_exp_f32_e32 v17, v17
	s_nop 0
	v_add_f32_e32 v17, 1.0, v17
	v_rcp_f32_e32 v20, v17
	v_mul_f32_e32 v17, 0x3d372713, v9
	v_mul_f32_e32 v17, v17, v9
	v_fma_mix_f32 v14, v17, v14, v14 op_sel:[0,1,1] op_sel_hi:[0,1,1]
	v_mul_f32_e32 v14, 0xc0135761, v14
	v_exp_f32_e32 v14, v14
	s_waitcnt lgkmcnt(0)
; #define LAS __attribute__((address_space(3)))
; __device__ __forceinline__ void sgu_item(const Params& P, LAS unsigned char* lds, int l, int item) {
;     ...
; #pragma unroll
;         for (int i = 0; i < 4; ++i) { const f16x8 u8 = *(const f16x8*)(up + 8 * i);
;             const f32x4 m0 = *(const LAS f32x4*)(mix + tk * 132 + 32 * q + 8 * i), m1 = *(const LAS f32x4*)(mix + tk * 132 + 32 * q + 8 * i + 4);
;             f16x8 o;
; #pragma unroll
;             for (int e = 0; e < 4; ++e) { o[e] = (f16)(gelu_fast((float)u8[e]) * (m0[e] + bst)); o[4 + e] = (f16)(gelu_fast((float)u8[4 + e]) * (m1[e] + bst)); }
;             *(f16x8*)(op + 8 * i) = o; }
	v_pk_add_f32 v[4:5], v[16:17], v[4:5] op_sel_hi:[0,1]
	v_pk_add_f32 v[6:7], v[16:17], v[6:7] op_sel_hi:[0,1]
	v_add_f32_e32 v14, 1.0, v14
	v_rcp_f32_e32 v21, v14
	s_nop 0
	v_pk_mul_f32 v[8:9], v[20:21], v[8:9]
	s_nop 0
	v_pk_mul_f32 v[4:5], v[4:5], v[8:9]
	s_nop 0
	v_cvt_pk_f16_f32 v14, v4, v5
	v_cvt_f32_f16_sdwa v5, v13 dst_sel:DWORD dst_unused:UNUSED_PAD src0_sel:WORD_1
	v_cvt_f32_f16_e32 v4, v13
	v_mul_f32_e32 v9, 0x3d372713, v5
	v_mul_f32_e32 v8, 0x3d372713, v4
	v_mul_f32_e32 v8, v8, v4
	v_mul_f32_e32 v9, v9, v5
	v_fma_mix_f32 v8, v8, v13, v13 op_sel_hi:[0,1,1]
	v_fma_mix_f32 v9, v9, v13, v13 op_sel:[0,1,1] op_sel_hi:[0,1,1]
	v_mul_f32_e32 v8, 0xc0135761, v8
	v_mul_f32_e32 v9, 0xc0135761, v9
	v_exp_f32_e32 v8, v8
	v_exp_f32_e32 v9, v9
	v_add_f32_e32 v8, 1.0, v8
	v_add_f32_e32 v9, 1.0, v9
	v_rcp_f32_e32 v8, v8
	v_rcp_f32_e32 v9, v9
	s_nop 0
	v_pk_mul_f32 v[4:5], v[8:9], v[4:5]
	v_pk_add_f32 v[8:9], v[16:17], v[10:11] op_sel_hi:[0,1]
	v_pk_mul_f32 v[4:5], v[8:9], v[4:5]
	s_nop 0
	v_cvt_pk_f16_f32 v13, v4, v5
	v_cvt_f32_f16_sdwa v5, v15 dst_sel:DWORD dst_unused:UNUSED_PAD src0_sel:WORD_1
	v_cvt_f32_f16_e32 v4, v15
	v_mul_f32_e32 v9, 0x3d372713, v5
	v_mul_f32_e32 v8, 0x3d372713, v4
	v_mul_f32_e32 v8, v8, v4
	v_mul_f32_e32 v9, v9, v5
	v_fma_mix_f32 v8, v8, v15, v15 op_sel_hi:[0,1,1]
	v_fma_mix_f32 v9, v9, v15, v15 op_sel:[0,1,1] op_sel_hi:[0,1,1]
	v_mul_f32_e32 v8, 0xc0135761, v8
	v_mul_f32_e32 v9, 0xc0135761, v9
	v_exp_f32_e32 v8, v8
	v_exp_f32_e32 v9, v9
	v_add_f32_e32 v8, 1.0, v8
	v_add_f32_e32 v9, 1.0, v9
	v_rcp_f32_e32 v8, v8
	v_rcp_f32_e32 v9, v9
	s_nop 0
	v_pk_mul_f32 v[4:5], v[8:9], v[4:5]
	s_nop 0
	v_pk_mul_f32 v[4:5], v[6:7], v[4:5]
	s_nop 0
	v_cvt_pk_f16_f32 v15, v4, v5
	v_mov_b32_e32 v4, v214
	v_mov_b32_e32 v5, v215
	v_mov_b32_e32 v6, v216
	v_mov_b32_e32 v7, v217
	s_nop 0
	v_cvt_f32_f16_e32 v20, v4
	v_cvt_f32_f16_sdwa v21, v4 dst_sel:DWORD dst_unused:UNUSED_PAD src0_sel:WORD_1
	global_store_dwordx4 v[18:19], v[12:15], off offset:16
	ds_read_b128 v[8:11], v2 offset:34880
	ds_read_b128 v[12:15], v2 offset:34896
	v_mul_f32_e32 v17, 0x3d372713, v20
	v_mul_f32_e32 v17, v17, v20
	v_fma_mix_f32 v17, v17, v4, v4 op_sel_hi:[0,1,1]
	v_mul_f32_e32 v17, 0xc0135761, v17
	v_exp_f32_e32 v17, v17
	s_nop 0
	v_add_f32_e32 v17, 1.0, v17
	v_rcp_f32_e32 v22, v17
	v_mul_f32_e32 v17, 0x3d372713, v21
	v_mul_f32_e32 v17, v17, v21
	v_fma_mix_f32 v4, v17, v4, v4 op_sel:[0,1,1] op_sel_hi:[0,1,1]
	v_mul_f32_e32 v4, 0xc0135761, v4
	v_exp_f32_e32 v4, v4
	s_waitcnt lgkmcnt(1)
	v_pk_add_f32 v[8:9], v[16:17], v[8:9] op_sel_hi:[0,1]
	v_add_f32_e32 v4, 1.0, v4
	v_rcp_f32_e32 v23, v4
	s_nop 0
	v_pk_mul_f32 v[20:21], v[22:23], v[20:21]
	s_nop 0
	v_pk_mul_f32 v[8:9], v[8:9], v[20:21]
	s_nop 0
	v_cvt_pk_f16_f32 v4, v8, v9
	v_cvt_f32_f16_e32 v8, v6
	v_cvt_f32_f16_sdwa v9, v6 dst_sel:DWORD dst_unused:UNUSED_PAD src0_sel:WORD_1
	v_mul_f32_e32 v17, 0x3d372713, v8
	v_mul_f32_e32 v17, v17, v8
	v_fma_mix_f32 v17, v17, v6, v6 op_sel_hi:[0,1,1]
	v_mul_f32_e32 v17, 0xc0135761, v17
	v_exp_f32_e32 v17, v17
	s_nop 0
	v_add_f32_e32 v17, 1.0, v17
	v_rcp_f32_e32 v20, v17
	v_mul_f32_e32 v17, 0x3d372713, v9
	v_mul_f32_e32 v17, v17, v9
	v_fma_mix_f32 v6, v17, v6, v6 op_sel:[0,1,1] op_sel_hi:[0,1,1]
	v_mul_f32_e32 v6, 0xc0135761, v6
	v_exp_f32_e32 v6, v6
	s_waitcnt lgkmcnt(0)
; #define LAS __attribute__((address_space(3)))
; __device__ __forceinline__ void sgu_item(const Params& P, LAS unsigned char* lds, int l, int item) {
;     ...
; #pragma unroll
;         for (int i = 0; i < 4; ++i) { const f16x8 u8 = *(const f16x8*)(up + 8 * i);
;             const f32x4 m0 = *(const LAS f32x4*)(mix + tk * 132 + 32 * q + 8 * i), m1 = *(const LAS f32x4*)(mix + tk * 132 + 32 * q + 8 * i + 4);
;             f16x8 o;
; #pragma unroll
;             for (int e = 0; e < 4; ++e) { o[e] = (f16)(gelu_fast((float)u8[e]) * (m0[e] + bst)); o[4 + e] = (f16)(gelu_fast((float)u8[4 + e]) * (m1[e] + bst)); }
;             *(f16x8*)(op + 8 * i) = o; }
;     }
;     __syncthreads();
	v_pk_add_f32 v[12:13], v[16:17], v[12:13] op_sel_hi:[0,1]
	v_pk_add_f32 v[10:11], v[16:17], v[10:11] op_sel_hi:[0,1]
	v_add_f32_e32 v6, 1.0, v6
	v_rcp_f32_e32 v21, v6
	s_nop 0
	v_pk_mul_f32 v[8:9], v[20:21], v[8:9]
	s_nop 0
	v_pk_mul_f32 v[8:9], v[12:13], v[8:9]
	s_nop 0
	v_cvt_pk_f16_f32 v6, v8, v9
	v_cvt_f32_f16_sdwa v9, v5 dst_sel:DWORD dst_unused:UNUSED_PAD src0_sel:WORD_1
	v_cvt_f32_f16_e32 v8, v5
	v_mul_f32_e32 v13, 0x3d372713, v9
	v_mul_f32_e32 v12, 0x3d372713, v8
	v_mul_f32_e32 v12, v12, v8
	v_mul_f32_e32 v13, v13, v9
	v_fma_mix_f32 v12, v12, v5, v5 op_sel_hi:[0,1,1]
	v_fma_mix_f32 v5, v13, v5, v5 op_sel:[0,1,1] op_sel_hi:[0,1,1]
	v_mul_f32_e32 v12, 0xc0135761, v12
	v_mul_f32_e32 v5, 0xc0135761, v5
	v_exp_f32_e32 v12, v12
	v_exp_f32_e32 v5, v5
	v_add_f32_e32 v12, 1.0, v12
	v_add_f32_e32 v5, 1.0, v5
	v_rcp_f32_e32 v12, v12
	v_rcp_f32_e32 v13, v5
	s_nop 0
	v_pk_mul_f32 v[8:9], v[12:13], v[8:9]
	s_nop 0
	v_pk_mul_f32 v[8:9], v[10:11], v[8:9]
	s_nop 0
	v_cvt_pk_f16_f32 v5, v8, v9
	v_cvt_f32_f16_sdwa v9, v7 dst_sel:DWORD dst_unused:UNUSED_PAD src0_sel:WORD_1
	v_cvt_f32_f16_e32 v8, v7
	v_mul_f32_e32 v11, 0x3d372713, v9
	v_mul_f32_e32 v10, 0x3d372713, v8
	v_mul_f32_e32 v10, v10, v8
	v_mul_f32_e32 v11, v11, v9
	v_fma_mix_f32 v10, v10, v7, v7 op_sel_hi:[0,1,1]
	v_fma_mix_f32 v7, v11, v7, v7 op_sel:[0,1,1] op_sel_hi:[0,1,1]
	v_mul_f32_e32 v10, 0xc0135761, v10
	v_mul_f32_e32 v7, 0xc0135761, v7
	v_exp_f32_e32 v10, v10
	v_exp_f32_e32 v7, v7
	v_add_f32_e32 v10, 1.0, v10
	v_add_f32_e32 v7, 1.0, v7
	v_rcp_f32_e32 v10, v10
	v_rcp_f32_e32 v11, v7
	s_nop 0
	v_pk_mul_f32 v[8:9], v[10:11], v[8:9]
	v_pk_add_f32 v[10:11], v[16:17], v[14:15] op_sel_hi:[0,1]
	v_pk_mul_f32 v[8:9], v[10:11], v[8:9]
	s_nop 0
	v_cvt_pk_f16_f32 v7, v8, v9
	v_mov_b32_e32 v8, v243
	v_mov_b32_e32 v9, v244
	v_mov_b32_e32 v10, v245
	v_mov_b32_e32 v11, v246
	s_nop 0
	v_cvt_f32_f16_e32 v20, v8
	global_store_dwordx4 v[18:19], v[4:7], off offset:32
	ds_read_b128 v[12:15], v2 offset:34912
	ds_read_b128 v[4:7], v2 offset:34928
	v_cvt_f32_f16_sdwa v21, v8 dst_sel:DWORD dst_unused:UNUSED_PAD src0_sel:WORD_1
	v_mul_f32_e32 v2, 0x3d372713, v20
	v_mul_f32_e32 v2, v2, v20
	v_fma_mix_f32 v2, v2, v8, v8 op_sel_hi:[0,1,1]
	v_mul_f32_e32 v2, 0xc0135761, v2
	v_exp_f32_e32 v2, v2
	s_waitcnt lgkmcnt(1)
	v_pk_add_f32 v[12:13], v[16:17], v[12:13] op_sel_hi:[0,1]
	s_waitcnt lgkmcnt(0)
	v_pk_add_f32 v[4:5], v[16:17], v[4:5] op_sel_hi:[0,1]
	v_pk_add_f32 v[6:7], v[16:17], v[6:7] op_sel_hi:[0,1]
	v_add_f32_e32 v2, 1.0, v2
	v_rcp_f32_e32 v22, v2
	v_mul_f32_e32 v2, 0x3d372713, v21
	v_mul_f32_e32 v2, v2, v21
	v_fma_mix_f32 v2, v2, v8, v8 op_sel:[0,1,1] op_sel_hi:[0,1,1]
	v_mul_f32_e32 v2, 0xc0135761, v2
	v_exp_f32_e32 v2, v2
	s_nop 0
	v_add_f32_e32 v2, 1.0, v2
	v_rcp_f32_e32 v23, v2
	s_nop 0
	v_pk_mul_f32 v[20:21], v[22:23], v[20:21]
	s_nop 0
	v_pk_mul_f32 v[12:13], v[12:13], v[20:21]
	s_nop 0
	v_cvt_pk_f16_f32 v8, v12, v13
	v_cvt_f32_f16_e32 v12, v10
	v_cvt_f32_f16_sdwa v13, v10 dst_sel:DWORD dst_unused:UNUSED_PAD src0_sel:WORD_1
	v_mul_f32_e32 v2, 0x3d372713, v12
	v_mul_f32_e32 v2, v2, v12
	v_fma_mix_f32 v2, v2, v10, v10 op_sel_hi:[0,1,1]
	v_mul_f32_e32 v2, 0xc0135761, v2
	v_exp_f32_e32 v2, v2
	s_nop 0
	v_add_f32_e32 v2, 1.0, v2
	v_rcp_f32_e32 v20, v2
	v_mul_f32_e32 v2, 0x3d372713, v13
	v_mul_f32_e32 v2, v2, v13
	v_fma_mix_f32 v2, v2, v10, v10 op_sel:[0,1,1] op_sel_hi:[0,1,1]
	v_mul_f32_e32 v2, 0xc0135761, v2
	v_exp_f32_e32 v2, v2
	s_nop 0
	v_add_f32_e32 v2, 1.0, v2
	v_rcp_f32_e32 v21, v2
	s_nop 0
	v_pk_mul_f32 v[12:13], v[20:21], v[12:13]
	s_nop 0
	v_pk_mul_f32 v[4:5], v[4:5], v[12:13]
	s_nop 0
	v_cvt_pk_f16_f32 v10, v4, v5
	v_cvt_f32_f16_e32 v4, v9
	v_cvt_f32_f16_sdwa v5, v9 dst_sel:DWORD dst_unused:UNUSED_PAD src0_sel:WORD_1
	v_mul_f32_e32 v2, 0x3d372713, v4
	v_mul_f32_e32 v2, v2, v4
	v_fma_mix_f32 v2, v2, v9, v9 op_sel_hi:[0,1,1]
	v_mul_f32_e32 v2, 0xc0135761, v2
	v_exp_f32_e32 v2, v2
	s_nop 0
	v_add_f32_e32 v2, 1.0, v2
	v_rcp_f32_e32 v12, v2
	v_mul_f32_e32 v2, 0x3d372713, v5
	v_mul_f32_e32 v2, v2, v5
	v_fma_mix_f32 v2, v2, v9, v9 op_sel:[0,1,1] op_sel_hi:[0,1,1]
	v_mul_f32_e32 v2, 0xc0135761, v2
	v_exp_f32_e32 v2, v2
	s_nop 0
	v_add_f32_e32 v2, 1.0, v2
	v_rcp_f32_e32 v13, v2
	s_nop 0
	v_pk_mul_f32 v[4:5], v[12:13], v[4:5]
	v_pk_add_f32 v[12:13], v[16:17], v[14:15] op_sel_hi:[0,1]
	v_pk_mul_f32 v[4:5], v[12:13], v[4:5]
	s_nop 0
	v_cvt_pk_f16_f32 v9, v4, v5
	v_cvt_f32_f16_e32 v4, v11
	v_cvt_f32_f16_sdwa v5, v11 dst_sel:DWORD dst_unused:UNUSED_PAD src0_sel:WORD_1
	v_mul_f32_e32 v2, 0x3d372713, v4
	v_mul_f32_e32 v2, v2, v4
	v_fma_mix_f32 v2, v2, v11, v11 op_sel_hi:[0,1,1]
	v_mul_f32_e32 v2, 0xc0135761, v2
	v_exp_f32_e32 v2, v2
	s_nop 0
	v_add_f32_e32 v2, 1.0, v2
	v_rcp_f32_e32 v12, v2
	v_mul_f32_e32 v2, 0x3d372713, v5
	v_mul_f32_e32 v2, v2, v5
	v_fma_mix_f32 v2, v2, v11, v11 op_sel:[0,1,1] op_sel_hi:[0,1,1]
	v_mul_f32_e32 v2, 0xc0135761, v2
	v_exp_f32_e32 v2, v2
	s_nop 0
	v_add_f32_e32 v2, 1.0, v2
	v_rcp_f32_e32 v13, v2
	s_nop 0
	v_pk_mul_f32 v[4:5], v[12:13], v[4:5]
	s_nop 0
	v_pk_mul_f32 v[4:5], v[6:7], v[4:5]
	s_nop 0
	v_cvt_pk_f16_f32 v11, v4, v5
	global_store_dwordx4 v[18:19], v[8:11], off offset:48
	s_barrier

; __device__ __forceinline__ void sgu_item(const Params& P, LAS unsigned char* lds, int l, int item) {
;     ...
;         const int tk = tid >> 2, q = tid & 3;
;         const f16* vp = p + (tok0 + tk) * NIN + 2 * GW + 128 * h + 32 * q;
;         const float* gp = P.sgu_norm_g + (size_t)l * GW + 128 * h + 32 * q;
;         f32x4 v[8]; float ss = 0.f;
; #pragma unroll
;         for (int i = 0; i < 4; ++i) { const f16x8 t = *(const f16x8*)(vp + 8 * i);
; #pragma unroll
;             for (int e = 0; e < 8; ++e) { const float gv = gelu_fast((float)t[e]); v[2 * i + (e >> 2)][e & 3] = gv; ss += gv * gv; } }
;     ...
;         const f16* up = p + (tok0 + tk) * NIN + GW + 128 * h + 32 * q;
;         f16* op = yraw + (tok0 + tk) * DM + GW + 128 * h + 32 * q;
; #pragma unroll
;         for (int i = 0; i < 4; ++i) { const f16x8 u8 = *(const f16x8*)(up + 8 * i);
.LBB0_951:
	s_andn2_b64 vcc, exec, s[0:1]
	s_cbranch_vccnz .LBB0_884
	s_addk_i32 s63, 0xfe80
	v_mov_b32_e32 v12, v0
	s_ashr_i32 s0, s63, 2
	s_ashr_i32 s1, s0, 31
	v_ashrrev_i32_e32 v30, 2, v12
	s_lshl_b64 s[0:1], s[0:1], 7
	v_ashrrev_i32_e32 v31, 31, v30
	v_lshl_add_u64 v[32:33], s[0:1], 0, v[30:31]
	v_readlane_b32 s0, v253, 0
	v_readlane_b32 s1, v253, 1
	s_waitcnt lgkmcnt(0)
	v_lshlrev_b32_e32 v2, 5, v12
	v_and_b32_e32 v34, 0x60, v2
	v_mov_b64_e32 v[4:5], s[0:1]
	v_mad_u64_u32 v[4:5], s[0:1], v32, s51, v[4:5]
	s_lshl_b32 s0, s63, 7
	s_and_b32 s18, s0, 0x180
	v_mad_i32_i24 v5, v33, s51, v5
	s_lshl_b32 s56, s18, 1
	v_lshl_add_u64 v[4:5], v[4:5], 0, s[56:57]
	v_lshlrev_b32_e32 v2, 1, v34
	v_lshl_add_u64 v[28:29], v[4:5], 0, v[2:3]
	global_load_dword v109, v[28:29], off offset:1024
	global_load_dword v207, v[28:29], off offset:1028
	global_load_dword v209, v[28:29], off offset:1032
	global_load_dword v211, v[28:29], off offset:1036
	global_load_dwordx4 v[180:183], v[28:29], off offset:1040
	global_load_dwordx4 v[214:217], v[28:29], off offset:1056
	global_load_dword v243, v[28:29], off offset:1072
	global_load_dwordx2 v[244:245], v[28:29], off offset:1076
	global_load_dword v246, v[28:29], off offset:1084
	global_load_dwordx4 v[8:11], v[28:29], off offset:2048
	global_load_dwordx4 v[24:27], v[28:29], off offset:2064
	global_load_dwordx4 v[4:7], v[28:29], off offset:2080
	s_lshl_b32 s0, s18, 2
	s_add_u32 s0, s52, s0
	s_addc_u32 s1, s53, 0
	v_lshlrev_b32_e32 v52, 2, v34
	v_bfe_u32 v105, v12, 5, 1
	v_readlane_b32 s64, v251, 10
	v_readlane_b32 s68, v251, 14
	v_readlane_b32 s69, v251, 15
	s_mov_b32 s19, 0
	s_mov_b64 s[8:9], -1
	s_movk_i32 s4, 0x210
	v_readlane_b32 s65, v251, 11
	v_readlane_b32 s66, v251, 12
	v_readlane_b32 s67, v251, 13
	v_readlane_b32 s70, v251, 16
	v_readlane_b32 s71, v251, 17
	v_readlane_b32 s72, v251, 18
	v_readlane_b32 s73, v251, 19
	v_readlane_b32 s74, v251, 20
	v_readlane_b32 s75, v251, 21
	v_readlane_b32 s76, v251, 22
	v_readlane_b32 s77, v251, 23
	v_readlane_b32 s78, v251, 24
	v_readlane_b32 s79, v251, 25
	s_waitcnt vmcnt(2)
	v_cvt_f32_f16_e32 v2, v8
	v_cvt_f32_f16_sdwa v13, v8 dst_sel:DWORD dst_unused:UNUSED_PAD src0_sel:WORD_1
	v_cvt_f32_f16_e32 v14, v9
	v_cvt_f32_f16_sdwa v15, v9 dst_sel:DWORD dst_unused:UNUSED_PAD src0_sel:WORD_1
	v_cvt_f32_f16_e32 v16, v10
	v_cvt_f32_f16_sdwa v19, v10 dst_sel:DWORD dst_unused:UNUSED_PAD src0_sel:WORD_1
	v_cvt_f32_f16_e32 v20, v11
	v_mul_f32_e32 v17, 0x3d372713, v2
	v_mul_f32_e32 v18, 0x3d372713, v13
	v_mul_f32_e32 v21, 0x3d372713, v14
	v_mul_f32_e32 v22, 0x3d372713, v15
	v_mul_f32_e32 v17, v17, v2
	v_mul_f32_e32 v18, v18, v13
	v_mul_f32_e32 v21, v21, v14
	v_mul_f32_e32 v22, v22, v15
	v_fma_mix_f32 v17, v17, v8, v8 op_sel_hi:[0,1,1]
	v_fma_mix_f32 v8, v18, v8, v8 op_sel:[0,1,1] op_sel_hi:[0,1,1]
	v_fma_mix_f32 v18, v21, v9, v9 op_sel_hi:[0,1,1]
	v_fma_mix_f32 v9, v22, v9, v9 op_sel:[0,1,1] op_sel_hi:[0,1,1]
	v_mul_f32_e32 v17, 0xc0135761, v17
	v_mul_f32_e32 v9, 0xc0135761, v9
	v_mul_f32_e32 v37, 0x3d372713, v16
	v_mul_f32_e32 v38, 0x3d372713, v19
	v_mul_f32_e32 v39, 0x3d372713, v20
	v_exp_f32_e32 v17, v17
	v_exp_f32_e32 v9, v9
	v_mul_f32_e32 v37, v37, v16
	v_mul_f32_e32 v38, v38, v19
	v_mul_f32_e32 v39, v39, v20
	v_fma_mix_f32 v21, v37, v10, v10 op_sel_hi:[0,1,1]
	v_fma_mix_f32 v10, v38, v10, v10 op_sel:[0,1,1] op_sel_hi:[0,1,1]
	v_fma_mix_f32 v22, v39, v11, v11 op_sel_hi:[0,1,1]
	v_mul_f32_e32 v18, 0xc0135761, v18
	v_mul_f32_e32 v10, 0xc0135761, v10
	v_mul_f32_e32 v22, 0xc0135761, v22
	v_exp_f32_e32 v18, v18
	v_exp_f32_e32 v10, v10
	v_exp_f32_e32 v22, v22
	v_add_f32_e32 v17, 1.0, v17
	v_add_f32_e32 v9, 1.0, v9
	v_rcp_f32_e32 v17, v17
	v_rcp_f32_e32 v9, v9
	v_mul_f32_e32 v8, 0xc0135761, v8
	v_exp_f32_e32 v8, v8
	v_add_f32_e32 v18, 1.0, v18
	v_add_f32_e32 v10, 1.0, v10
	v_add_f32_e32 v22, 1.0, v22
	v_cvt_f32_f16_sdwa v23, v11 dst_sel:DWORD dst_unused:UNUSED_PAD src0_sel:WORD_1
	v_rcp_f32_e32 v18, v18
	v_rcp_f32_e32 v10, v10
	v_rcp_f32_e32 v39, v22
	v_mul_f32_e32 v22, v17, v2
	v_mul_f32_e32 v17, v9, v15
	s_waitcnt vmcnt(1)
	v_cvt_f32_f16_e32 v9, v25
	v_mul_f32_e32 v21, 0xc0135761, v21
	v_exp_f32_e32 v21, v21
	v_add_f32_e32 v8, 1.0, v8
	v_cvt_f32_f16_sdwa v36, v24 dst_sel:DWORD dst_unused:UNUSED_PAD src0_sel:WORD_1
	v_mul_f32_e32 v40, 0x3d372713, v23
	v_rcp_f32_e32 v8, v8
	v_mul_f32_e32 v18, v18, v14
	v_mul_f32_e32 v14, v10, v19
	v_mul_f32_e32 v10, 0x3d372713, v9
	v_mul_f32_e32 v40, v40, v23
	v_mul_f32_e32 v10, v10, v9
	v_fma_mix_f32 v11, v40, v11, v11 op_sel:[0,1,1] op_sel_hi:[0,1,1]
	v_fma_mix_f32 v10, v10, v25, v25 op_sel_hi:[0,1,1]
	v_mul_f32_e32 v11, 0xc0135761, v11
	v_add_f32_e32 v21, 1.0, v21
	v_mul_f32_e32 v10, 0xc0135761, v10
	v_exp_f32_e32 v11, v11
	v_rcp_f32_e32 v38, v21
	v_mul_f32_e32 v21, v8, v13
	v_mul_f32_e32 v8, 0x3d372713, v36
	v_exp_f32_e32 v10, v10
	v_mul_f32_e32 v8, v8, v36
	v_fma_mix_f32 v8, v8, v24, v24 op_sel:[0,1,1] op_sel_hi:[0,1,1]
	v_mul_f32_e32 v8, 0xc0135761, v8
	v_add_f32_e32 v11, 1.0, v11
	v_exp_f32_e32 v8, v8
	v_add_f32_e32 v10, 1.0, v10
	v_rcp_f32_e32 v11, v11
	v_rcp_f32_e32 v10, v10
	v_add_f32_e32 v8, 1.0, v8
	v_rcp_f32_e32 v8, v8
	v_mul_f32_e32 v15, v11, v23
	v_cvt_f32_f16_sdwa v11, v25 dst_sel:DWORD dst_unused:UNUSED_PAD src0_sel:WORD_1
	v_mul_f32_e32 v19, v10, v9
	v_cvt_f32_f16_e32 v9, v26
	v_mul_f32_e32 v2, v39, v20
	v_mul_f32_e32 v20, v8, v36
	v_mul_f32_e32 v8, 0x3d372713, v11
	v_mul_f32_e32 v10, 0x3d372713, v9
	v_mul_f32_e32 v8, v8, v11
	v_mul_f32_e32 v10, v10, v9
	v_fma_mix_f32 v8, v8, v25, v25 op_sel:[0,1,1] op_sel_hi:[0,1,1]
	v_fma_mix_f32 v10, v10, v26, v26 op_sel_hi:[0,1,1]
	v_mul_f32_e32 v8, 0xc0135761, v8
	v_mul_f32_e32 v10, 0xc0135761, v10
; __device__ __forceinline__ void sgu_item(const Params& P, LAS unsigned char* lds, int l, int item) {
;     ...
;         f32x4 v[8]; float ss = 0.f;
; #pragma unroll
;         for (int i = 0; i < 4; ++i) { const f16x8 t = *(const f16x8*)(vp + 8 * i);
; #pragma unroll
;             for (int e = 0; e < 8; ++e) { const float gv = gelu_fast((float)t[e]); v[2 * i + (e >> 2)][e & 3] = gv; ss += gv * gv; } }
	v_exp_f32_e32 v8, v8
	v_exp_f32_e32 v10, v10
	v_cvt_f32_f16_e32 v35, v24
	v_cvt_f32_f16_sdwa v25, v26 dst_sel:DWORD dst_unused:UNUSED_PAD src0_sel:WORD_1
	v_add_f32_e32 v8, 1.0, v8
	v_add_f32_e32 v10, 1.0, v10
	v_mul_f32_e32 v41, 0x3d372713, v35
	v_rcp_f32_e32 v8, v8
	v_rcp_f32_e32 v10, v10
	v_mul_f32_e32 v41, v41, v35
	v_fma_mix_f32 v37, v41, v24, v24 op_sel_hi:[0,1,1]
	v_mul_f32_e32 v37, 0xc0135761, v37
	v_exp_f32_e32 v37, v37
	v_mul_f32_e32 v24, v8, v11
	v_mul_f32_e32 v23, v10, v9
	v_mul_f32_e32 v8, 0x3d372713, v25
	v_cvt_f32_f16_e32 v9, v27
	v_mul_f32_e32 v8, v8, v25
	v_fma_mix_f32 v8, v8, v26, v26 op_sel:[0,1,1] op_sel_hi:[0,1,1]
	v_mul_f32_e32 v8, 0xc0135761, v8
	v_add_f32_e32 v37, 1.0, v37
	v_exp_f32_e32 v8, v8
	v_mul_f32_e32 v10, 0x3d372713, v9
	v_rcp_f32_e32 v37, v37
	v_mul_f32_e32 v10, v10, v9
	v_fma_mix_f32 v10, v10, v27, v27 op_sel_hi:[0,1,1]
	v_mul_f32_e32 v10, 0xc0135761, v10
	v_exp_f32_e32 v10, v10
	v_add_f32_e32 v8, 1.0, v8
	v_mul_f32_e32 v13, v37, v35
	v_rcp_f32_e32 v8, v8
	v_cvt_f32_f16_sdwa v35, v27 dst_sel:DWORD dst_unused:UNUSED_PAD src0_sel:WORD_1
	v_add_f32_e32 v10, 1.0, v10
	v_rcp_f32_e32 v10, v10
	v_mul_f32_e32 v26, v8, v25
	v_mul_f32_e32 v8, 0x3d372713, v35
	v_mul_f32_e32 v8, v8, v35
	v_fma_mix_f32 v8, v8, v27, v27 op_sel:[0,1,1] op_sel_hi:[0,1,1]
	v_mul_f32_e32 v8, 0xc0135761, v8
	v_mul_f32_e32 v25, v10, v9
	v_exp_f32_e32 v27, v8
	global_load_dwordx4 v[8:11], v[28:29], off offset:2096
	s_waitcnt vmcnt(1)
	v_cvt_f32_f16_e32 v36, v4
	v_mul_f32_e32 v16, v38, v16
	v_add_f32_e32 v27, 1.0, v27
	v_rcp_f32_e32 v27, v27
	v_mul_f32_e32 v37, 0x3d372713, v36
	v_mul_f32_e32 v37, v37, v36
	v_fma_mix_f32 v37, v37, v4, v4 op_sel_hi:[0,1,1]
	v_mul_f32_e32 v37, 0xc0135761, v37
	v_exp_f32_e32 v37, v37
	v_mul_f32_e32 v27, v27, v35
	v_cvt_f32_f16_sdwa v35, v4 dst_sel:DWORD dst_unused:UNUSED_PAD src0_sel:WORD_1
	v_mul_f32_e32 v40, v21, v21
	v_add_f32_e32 v37, 1.0, v37
	v_rcp_f32_e32 v37, v37
	v_mul_f32_e32 v38, 0x3d372713, v35
	v_mul_f32_e32 v38, v38, v35
	v_fma_mix_f32 v4, v38, v4, v4 op_sel:[0,1,1] op_sel_hi:[0,1,1]
	v_mul_f32_e32 v4, 0xc0135761, v4
	v_exp_f32_e32 v4, v4
	v_mul_f32_e32 v56, v37, v36
	v_cvt_f32_f16_e32 v36, v5
	v_fmac_f32_e32 v40, v22, v22
	v_add_f32_e32 v4, 1.0, v4
	v_rcp_f32_e32 v4, v4
	v_mul_f32_e32 v37, 0x3d372713, v36
	v_mul_f32_e32 v37, v37, v36
	v_fma_mix_f32 v37, v37, v5, v5 op_sel_hi:[0,1,1]
	v_mul_f32_e32 v37, 0xc0135761, v37
	v_exp_f32_e32 v37, v37
	v_mul_f32_e32 v35, v4, v35
	v_cvt_f32_f16_sdwa v4, v5 dst_sel:DWORD dst_unused:UNUSED_PAD src0_sel:WORD_1
	v_fmac_f32_e32 v40, v18, v18
	v_add_f32_e32 v37, 1.0, v37
	v_rcp_f32_e32 v37, v37
	v_mul_f32_e32 v38, 0x3d372713, v4
	v_mul_f32_e32 v38, v38, v4
	v_fma_mix_f32 v5, v38, v5, v5 op_sel:[0,1,1] op_sel_hi:[0,1,1]
	v_mul_f32_e32 v5, 0xc0135761, v5
	v_exp_f32_e32 v5, v5
	v_mul_f32_e32 v57, v37, v36
	v_cvt_f32_f16_e32 v36, v6
	v_fmac_f32_e32 v40, v17, v17
	v_add_f32_e32 v5, 1.0, v5
	v_rcp_f32_e32 v5, v5
	v_mul_f32_e32 v37, 0x3d372713, v36
	v_mul_f32_e32 v37, v37, v36
	v_fma_mix_f32 v37, v37, v6, v6 op_sel_hi:[0,1,1]
	v_mul_f32_e32 v37, 0xc0135761, v37
	v_exp_f32_e32 v37, v37
	v_mul_f32_e32 v58, v5, v4
	v_cvt_f32_f16_sdwa v4, v6 dst_sel:DWORD dst_unused:UNUSED_PAD src0_sel:WORD_1
	v_fmac_f32_e32 v40, v16, v16
	v_add_f32_e32 v5, 1.0, v37
	v_rcp_f32_e32 v5, v5
	v_mul_f32_e32 v37, 0x3d372713, v4
	v_mul_f32_e32 v37, v37, v4
	v_fma_mix_f32 v6, v37, v6, v6 op_sel:[0,1,1] op_sel_hi:[0,1,1]
	v_mul_f32_e32 v6, 0xc0135761, v6
	v_exp_f32_e32 v6, v6
	v_mul_f32_e32 v59, v5, v36
	v_cvt_f32_f16_e32 v5, v7
	v_fmac_f32_e32 v40, v14, v14
	v_add_f32_e32 v6, 1.0, v6
	v_rcp_f32_e32 v6, v6
	v_mul_f32_e32 v36, 0x3d372713, v5
	v_mul_f32_e32 v36, v36, v5
	v_fma_mix_f32 v36, v36, v7, v7 op_sel_hi:[0,1,1]
	v_mul_f32_e32 v36, 0xc0135761, v36
	v_exp_f32_e32 v36, v36
	v_mul_f32_e32 v60, v6, v4
	v_cvt_f32_f16_sdwa v4, v7 dst_sel:DWORD dst_unused:UNUSED_PAD src0_sel:WORD_1
	v_fmac_f32_e32 v40, v2, v2
	v_add_f32_e32 v6, 1.0, v36
	v_rcp_f32_e32 v6, v6
	v_mul_f32_e32 v36, 0x3d372713, v4
	v_mul_f32_e32 v36, v36, v4
	v_fma_mix_f32 v7, v36, v7, v7 op_sel:[0,1,1] op_sel_hi:[0,1,1]
	v_mul_f32_e32 v7, 0xc0135761, v7
	v_exp_f32_e32 v7, v7
	v_mul_f32_e32 v61, v6, v5
	s_waitcnt vmcnt(0)
	v_cvt_f32_f16_e32 v5, v8
	v_fmac_f32_e32 v40, v15, v15
	v_add_f32_e32 v6, 1.0, v7
	v_rcp_f32_e32 v6, v6
	v_mul_f32_e32 v7, 0x3d372713, v5
	v_mul_f32_e32 v7, v7, v5
	v_fma_mix_f32 v7, v7, v8, v8 op_sel_hi:[0,1,1]
	v_mul_f32_e32 v7, 0xc0135761, v7
	v_exp_f32_e32 v7, v7
	v_mul_f32_e32 v62, v6, v4
	v_cvt_f32_f16_sdwa v4, v8 dst_sel:DWORD dst_unused:UNUSED_PAD src0_sel:WORD_1
	v_fmac_f32_e32 v40, v13, v13
	v_add_f32_e32 v6, 1.0, v7
	v_rcp_f32_e32 v6, v6
	v_mul_f32_e32 v7, 0x3d372713, v4
	v_mul_f32_e32 v7, v7, v4
	v_fma_mix_f32 v7, v7, v8, v8 op_sel:[0,1,1] op_sel_hi:[0,1,1]
	v_mul_f32_e32 v7, 0xc0135761, v7
	v_exp_f32_e32 v7, v7
	v_mul_f32_e32 v63, v6, v5
	v_cvt_f32_f16_e32 v5, v9
	v_cvt_f32_f16_sdwa v8, v10 dst_sel:DWORD dst_unused:UNUSED_PAD src0_sel:WORD_1
	v_add_f32_e32 v6, 1.0, v7
	v_rcp_f32_e32 v6, v6
	v_mul_f32_e32 v7, 0x3d372713, v5
	v_mul_f32_e32 v7, v7, v5
	v_fma_mix_f32 v7, v7, v9, v9 op_sel_hi:[0,1,1]
	v_mul_f32_e32 v7, 0xc0135761, v7
	v_exp_f32_e32 v7, v7
	v_mul_f32_e32 v64, v6, v4
	v_cvt_f32_f16_sdwa v4, v9 dst_sel:DWORD dst_unused:UNUSED_PAD src0_sel:WORD_1
	v_fmac_f32_e32 v40, v20, v20
	v_add_f32_e32 v6, 1.0, v7
	v_rcp_f32_e32 v6, v6
	v_mul_f32_e32 v7, 0x3d372713, v4
	v_mul_f32_e32 v7, v7, v4
	v_fma_mix_f32 v7, v7, v9, v9 op_sel:[0,1,1] op_sel_hi:[0,1,1]
	v_mul_f32_e32 v7, 0xc0135761, v7
	v_exp_f32_e32 v7, v7
	v_mul_f32_e32 v65, v6, v5
	v_cvt_f32_f16_e32 v5, v10
	v_cvt_f32_f16_e32 v9, v11
	v_add_f32_e32 v6, 1.0, v7
; __device__ __forceinline__ void sgu_item(const Params& P, LAS unsigned char* lds, int l, int item) {
;     ...
;         ss += __shfl_xor(ss, 1); ss += __shfl_xor(ss, 2);
;         const float rstd = 1.0f / sqrtf(ss * (1.0f / HD) + EPS);
; #pragma unroll
;         for (int i = 0; i < 8; ++i) { const f32x4 gg = *(const f32x4*)(gp + 4 * i); const f32x4 y = (v[i] * rstd) * gg;
; #pragma unroll
;             for (int e = 0; e < 4; ++e) vhT[(32 * q + 4 * i + e) * 136 + tk] = (f16)y[e]; }
	v_rcp_f32_e32 v6, v6
	v_mul_f32_e32 v7, 0x3d372713, v5
	v_mul_f32_e32 v7, v7, v5
	v_fma_mix_f32 v7, v7, v10, v10 op_sel_hi:[0,1,1]
	v_mul_f32_e32 v7, 0xc0135761, v7
	v_exp_f32_e32 v7, v7
	v_mul_f32_e32 v66, v6, v4
	v_mul_f32_e32 v6, 0x3d372713, v8
	v_mul_f32_e32 v6, v6, v8
	v_fma_mix_f32 v6, v6, v10, v10 op_sel:[0,1,1] op_sel_hi:[0,1,1]
	v_add_f32_e32 v4, 1.0, v7
	v_mul_f32_e32 v6, 0xc0135761, v6
	v_rcp_f32_e32 v4, v4
	v_exp_f32_e32 v6, v6
	v_fmac_f32_e32 v40, v19, v19
	v_fmac_f32_e32 v40, v24, v24
	v_mul_f32_e32 v67, v4, v5
	v_add_f32_e32 v4, 1.0, v6
	v_rcp_f32_e32 v10, v4
	v_mul_f32_e32 v4, 0x3d372713, v9
	v_mul_f32_e32 v4, v4, v9
	v_fma_mix_f32 v4, v4, v11, v11 op_sel_hi:[0,1,1]
	v_mul_f32_e32 v4, 0xc0135761, v4
	v_exp_f32_e32 v41, v4
	global_load_dwordx4 v[4:7], v52, s[0:1] offset:16
	global_load_dwordx4 v[36:39], v52, s[0:1]
	v_fmac_f32_e32 v40, v23, v23
	v_fmac_f32_e32 v40, v26, v26
	v_cvt_f32_f16_sdwa v42, v11 dst_sel:DWORD dst_unused:UNUSED_PAD src0_sel:WORD_1
	v_fmac_f32_e32 v40, v25, v25
	v_fmac_f32_e32 v40, v27, v27
	v_fmac_f32_e32 v40, v56, v56
	v_fmac_f32_e32 v40, v35, v35
	v_mul_f32_e32 v43, 0x3d372713, v42
	v_fmac_f32_e32 v40, v57, v57
	v_mul_f32_e32 v43, v43, v42
	v_fmac_f32_e32 v40, v58, v58
	v_fma_mix_f32 v11, v43, v11, v11 op_sel:[0,1,1] op_sel_hi:[0,1,1]
	v_fmac_f32_e32 v40, v59, v59
	v_mul_f32_e32 v11, 0xc0135761, v11
	v_fmac_f32_e32 v40, v60, v60
	v_exp_f32_e32 v11, v11
	v_fmac_f32_e32 v40, v61, v61
	v_mul_f32_e32 v68, v10, v8
	v_add_f32_e32 v8, 1.0, v41
	v_fmac_f32_e32 v40, v62, v62
	v_rcp_f32_e32 v8, v8
	v_fmac_f32_e32 v40, v63, v63
	v_fmac_f32_e32 v40, v64, v64
	v_add_f32_e32 v10, 1.0, v11
	v_fmac_f32_e32 v40, v65, v65
	v_rcp_f32_e32 v10, v10
	v_fmac_f32_e32 v40, v66, v66
	v_mul_f32_e32 v69, v8, v9
	v_and_b32_e32 v9, 64, v238
	v_fmac_f32_e32 v40, v67, v67
	v_xor_b32_e32 v8, 1, v238
	v_add_u32_e32 v9, 64, v9
	v_fmac_f32_e32 v40, v68, v68
	v_cmp_lt_i32_e32 vcc, v8, v9
	v_fmac_f32_e32 v40, v69, v69
	v_mul_f32_e32 v70, v10, v42
	v_cndmask_b32_e32 v8, v238, v8, vcc
	v_fmac_f32_e32 v40, v70, v70
	v_lshlrev_b32_e32 v8, 2, v8
	ds_bpermute_b32 v8, v8, v40
	s_waitcnt lgkmcnt(0)
	v_add_f32_e32 v40, v40, v8
	v_xor_b32_e32 v8, 2, v238
	v_cmp_lt_i32_e32 vcc, v8, v9
	s_nop 1
	v_cndmask_b32_e32 v8, v238, v8, vcc
	v_lshlrev_b32_e32 v8, 2, v8
	ds_bpermute_b32 v41, v8, v40
	global_load_dwordx4 v[8:11], v52, s[0:1] offset:32
	s_waitcnt lgkmcnt(0)
	v_add_f32_e32 v40, v40, v41
	v_fmamk_f32 v40, v40, 0x3c000000, v234
	v_mul_f32_e32 v41, 0x4f800000, v40
	v_cmp_gt_f32_e32 vcc, s83, v40
	s_nop 1
	v_cndmask_b32_e32 v44, v40, v41, vcc
	v_sqrt_f32_e32 v45, v44
	global_load_dwordx4 v[40:43], v52, s[0:1] offset:48
	v_add_u32_e32 v46, -1, v45
	v_fma_f32 v47, -v46, v45, v44
	v_cmp_ge_f32_e64 s[46:47], 0, v47
	v_add_u32_e32 v47, 1, v45
	s_nop 0
	v_cndmask_b32_e64 v46, v45, v46, s[46:47]
	v_fma_f32 v45, -v47, v45, v44
	v_cmp_lt_f32_e64 s[46:47], 0, v45
	s_nop 1
	v_cndmask_b32_e64 v45, v46, v47, s[46:47]
	v_mul_f32_e32 v46, 0x37800000, v45
	v_cndmask_b32_e32 v45, v45, v46, vcc
	v_cmp_class_f32_e32 vcc, v44, v235
	s_nop 1
	v_cndmask_b32_e32 v53, v45, v44, vcc
	v_div_scale_f32 v54, s[2:3], v53, v53, 1.0
	v_rcp_f32_e32 v55, v54
	v_div_scale_f32 v71, vcc, 1.0, v53, 1.0
	v_readfirstlane_b32 s2, v12
	v_fma_f32 v44, -v54, v55, 1.0
	v_fmac_f32_e32 v55, v44, v55
	global_load_dwordx4 v[44:47], v52, s[0:1] offset:80
	global_load_dwordx4 v[48:51], v52, s[0:1] offset:64
	v_mul_f32_e32 v72, v71, v55
	v_fma_f32 v73, -v54, v72, v71
	v_fmac_f32_e32 v72, v73, v55
	v_fma_f32 v54, -v54, v72, v71
	v_div_fmas_f32 v54, v54, v55, v72
	v_div_fixup_f32 v71, v54, v53, 1.0
	v_mul_f32_e32 v22, v22, v71
	v_lshlrev_b32_e32 v53, 1, v30
	s_waitcnt vmcnt(4)
	v_fma_mixlo_f16 v22, v36, v22, 0
	v_mul_u32_u24_e32 v36, 0x110, v34
	v_mul_f32_e32 v21, v21, v71
	v_mul_f32_e32 v18, v18, v71
	v_mul_f32_e32 v17, v17, v71
	v_add3_u32 v72, 0, v53, v36
	v_fma_mixlo_f16 v21, v37, v21, 0
	v_fma_mixlo_f16 v18, v38, v18, 0
	v_fma_mixlo_f16 v17, v39, v17, 0
	ds_write_b16 v72, v22
	ds_write_b16 v72, v21 offset:272
	ds_write_b16 v72, v18 offset:544
	ds_write_b16 v72, v17 offset:816
	global_load_dwordx4 v[36:39], v52, s[0:1] offset:112
	s_nop 0
	global_load_dwordx4 v[52:55], v52, s[0:1] offset:96
	v_mul_f32_e32 v2, v2, v71
	v_fma_mixlo_f16 v2, v6, v2, 0
	ds_write_b16 v72, v2 offset:1632
	v_mul_f32_e32 v2, v15, v71
	v_fma_mixlo_f16 v2, v7, v2, 0
	ds_write_b16 v72, v2 offset:1904
	v_mul_f32_e32 v2, v13, v71
	v_mul_f32_e32 v16, v16, v71
	s_cmpk_gt_u32 s2, 0xff
	v_fma_mixlo_f16 v4, v4, v16, 0
	s_cselect_b64 s[0:1], -1, 0
	s_lshr_b32 s2, s2, 1
	ds_write_b16 v72, v4 offset:1088
	v_mul_f32_e32 v4, v14, v71
	s_and_b32 s2, s2, 0x60
	v_fma_mixlo_f16 v4, v5, v4, 0
	ds_write_b16 v72, v4 offset:1360
	s_waitcnt vmcnt(5)
; #define LAS __attribute__((address_space(3)))
; __device__ __forceinline__ void sgu_item(const Params& P, LAS unsigned char* lds, int l, int item) {
;     ...
;         for (int i = 0; i < 8; ++i) { const f32x4 gg = *(const f32x4*)(gp + 4 * i); const f32x4 y = (v[i] * rstd) * gg;
; #pragma unroll
;             for (int e = 0; e < 4; ++e) vhT[(32 * q + 4 * i + e) * 136 + tk] = (f16)y[e]; }
;     }
;     __syncthreads();
;     const int cb = wave & 3, pr = wave >> 2;
; #pragma unroll 1
;     for (int ti = 0; ti < 2; ++ti) {
;         const int tb = pr ? (1 + ti) : (3 * ti), t = 32 * tb + ln;
;         f32x16 acc;
; #pragma unroll
;         for (int r = 0; r < 16; ++r) acc[r] = 0.f;
;         const float* wrow = P.sgu_w + (((size_t)l * NH + h) * 128 + t) * 128 + 8 * hf;
;         const LAS f16* vrow = vhT + (32 * cb + ln) * 136 + 8 * hf;
	v_fma_mixlo_f16 v2, v8, v2, 0
	ds_write_b16 v72, v2 offset:2176
	v_mul_f32_e32 v2, v20, v71
	v_fma_mixlo_f16 v2, v9, v2, 0
	ds_write_b16 v72, v2 offset:2448
	v_mul_f32_e32 v2, v19, v71
	v_fma_mixlo_f16 v2, v10, v2, 0
	ds_write_b16 v72, v2 offset:2720
	v_mul_f32_e32 v2, v24, v71
	v_fma_mixlo_f16 v2, v11, v2, 0
	ds_write_b16 v72, v2 offset:2992
	v_mul_f32_e32 v2, v23, v71
	s_waitcnt vmcnt(4)
	v_fma_mixlo_f16 v2, v40, v2, 0
	ds_write_b16 v72, v2 offset:3264
	v_mul_f32_e32 v2, v26, v71
	v_fma_mixlo_f16 v2, v41, v2, 0
	ds_write_b16 v72, v2 offset:3536
	v_mul_f32_e32 v2, v25, v71
	v_fma_mixlo_f16 v2, v42, v2, 0
	ds_write_b16 v72, v2 offset:3808
	v_mul_f32_e32 v2, v27, v71
	v_fma_mixlo_f16 v2, v43, v2, 0
	ds_write_b16 v72, v2 offset:4080
	v_mul_f32_e32 v2, v56, v71
	v_lshlrev_b32_e32 v4, 4, v105
	v_lshlrev_b32_e32 v40, 3, v105
	s_or_b32 s3, s30, s18
	v_or_b32_e32 v43, 4, v40
	v_or_b32_e32 v56, 23, v40
	v_or_b32_e32 v73, 64, v40
	v_or_b32_e32 v74, 0x44, v40
	v_or_b32_e32 v75, 0x41, v40
	v_or_b32_e32 v76, 0x45, v40
	v_or_b32_e32 v77, 0x42, v40
	v_or_b32_e32 v78, 0x46, v40
	v_or_b32_e32 v79, 0x43, v40
	v_or_b32_e32 v80, 0x47, v40
	v_or_b32_e32 v81, 0x50, v40
	v_or_b32_e32 v82, 0x54, v40
	v_or_b32_e32 v83, 0x51, v40
	s_waitcnt vmcnt(2)
	v_fma_mixlo_f16 v2, v48, v2, 0
	ds_write_b16 v72, v2 offset:4352
	v_mul_f32_e32 v2, v35, v71
	v_fma_mixlo_f16 v2, v49, v2, 0
	ds_write_b16 v72, v2 offset:4624
	v_mul_f32_e32 v2, v57, v71
	v_fma_mixlo_f16 v2, v50, v2, 0
	ds_write_b16 v72, v2 offset:4896
	v_mul_f32_e32 v2, v58, v71
	v_fma_mixlo_f16 v2, v51, v2, 0
	ds_write_b16 v72, v2 offset:5168
	v_mul_f32_e32 v2, v59, v71
	v_fma_mixlo_f16 v2, v44, v2, 0
	ds_write_b16 v72, v2 offset:5440
	v_mul_f32_e32 v2, v60, v71
	v_fma_mixlo_f16 v2, v45, v2, 0
	ds_write_b16 v72, v2 offset:5712
	v_mul_f32_e32 v2, v61, v71
	v_fma_mixlo_f16 v2, v46, v2, 0
	ds_write_b16 v72, v2 offset:5984
	v_mul_f32_e32 v2, v62, v71
	v_fma_mixlo_f16 v2, v47, v2, 0
	ds_write_b16 v72, v2 offset:6256
	v_mul_f32_e32 v2, v63, v71
	s_waitcnt vmcnt(0)
	v_fma_mixlo_f16 v2, v52, v2, 0
	ds_write_b16 v72, v2 offset:6528
	v_mul_f32_e32 v2, v64, v71
	v_fma_mixlo_f16 v2, v53, v2, 0
	ds_write_b16 v72, v2 offset:6800
	v_mul_f32_e32 v2, v65, v71
	v_fma_mixlo_f16 v2, v54, v2, 0
	ds_write_b16 v72, v2 offset:7072
	v_mul_f32_e32 v2, v66, v71
	v_fma_mixlo_f16 v2, v55, v2, 0
	ds_write_b16 v72, v2 offset:7344
	v_mul_f32_e32 v2, v67, v71
	v_fma_mixlo_f16 v2, v36, v2, 0
	ds_write_b16 v72, v2 offset:7616
	v_mul_f32_e32 v2, v68, v71
	v_fma_mixlo_f16 v2, v37, v2, 0
	ds_write_b16 v72, v2 offset:7888
	v_mul_f32_e32 v2, v69, v71
	v_fma_mixlo_f16 v2, v38, v2, 0
	ds_write_b16 v72, v2 offset:8160
	v_mul_f32_e32 v2, v70, v71
	v_fma_mixlo_f16 v2, v39, v2, 0
	v_and_b32_e32 v35, 31, v12
	ds_write_b16 v72, v2 offset:8432
	v_or_b32_e32 v2, s2, v35
	v_mul_u32_u24_e32 v2, 0x110, v2
	s_lshl_b32 s2, s2, 2
	v_add3_u32 v41, 0, v2, v4
	s_add_i32 s2, s2, 0
	v_lshlrev_b32_e32 v2, 5, v105
	v_add_u32_e32 v42, s2, v4
	v_or_b32_e32 v44, 5, v40
	v_or_b32_e32 v45, 2, v40
	v_or_b32_e32 v46, 6, v40
	v_or_b32_e32 v47, 3, v40
	v_or_b32_e32 v48, 7, v40
	v_or_b32_e32 v49, 16, v40
	v_or_b32_e32 v50, 20, v40
	v_or_b32_e32 v51, 17, v40
	v_or_b32_e32 v52, 21, v40
	v_or_b32_e32 v53, 18, v40
	v_or_b32_e32 v54, 22, v40
	v_or_b32_e32 v55, 19, v40
	v_or_b32_e32 v57, 32, v40
	v_or_b32_e32 v58, 36, v40
	v_or_b32_e32 v59, 33, v40
	v_or_b32_e32 v60, 37, v40
	v_or_b32_e32 v61, 34, v40
	v_or_b32_e32 v62, 38, v40
	v_or_b32_e32 v63, 35, v40
	v_or_b32_e32 v64, 39, v40
	v_or_b32_e32 v65, 48, v40
	v_or_b32_e32 v66, 52, v40
	v_or_b32_e32 v67, 49, v40
	v_or_b32_e32 v68, 53, v40
	v_or_b32_e32 v69, 50, v40
	v_or_b32_e32 v70, 54, v40
	v_or_b32_e32 v71, 51, v40
	v_or_b32_e32 v72, 55, v40
	v_or_b32_e32 v84, 0x55, v40
	v_or_b32_e32 v85, 0x52, v40
	v_or_b32_e32 v86, 0x56, v40
	v_or_b32_e32 v87, 0x53, v40
	v_or_b32_e32 v88, 0x57, v40
	v_or_b32_e32 v89, 0x60, v40
	v_or_b32_e32 v90, 0x64, v40
	v_or_b32_e32 v91, 0x61, v40
	v_or_b32_e32 v92, 0x65, v40
	v_or_b32_e32 v93, 0x62, v40
	v_or_b32_e32 v94, 0x66, v40
	v_or_b32_e32 v95, 0x63, v40
	v_or_b32_e32 v96, 0x67, v40
	v_or_b32_e32 v97, 0x70, v40
	v_or_b32_e32 v98, 0x74, v40
	v_or_b32_e32 v99, 0x71, v40
	v_or_b32_e32 v100, 0x75, v40
	v_or_b32_e32 v101, 0x72, v40
	v_or_b32_e32 v102, 0x76, v40
	v_or_b32_e32 v103, 0x73, v40
	v_or_b32_e32 v104, 0x77, v40
	v_lshl_add_u64 v[36:37], s[68:69], 0, v[2:3]
	s_waitcnt lgkmcnt(0)
	s_barrier
	s_branch .LBB0_954
